# scan chunk loops: first-step operand LDS reads issued right behind the chunk barrier / at chunk-loop top, ahead of the scalar token bookkeeping
# baseline (speedup 1.0000x reference)
.LBB0_853:
	s_waitcnt lgkmcnt(11)
	ds_read_b128 v[22:25], v100
	s_waitcnt lgkmcnt(11)
	ds_read_b128 v[18:21], v100 offset:16
	s_waitcnt lgkmcnt(11)
	ds_read_b128 v[2:5], v100 offset:256
	s_waitcnt lgkmcnt(11)
	ds_read_b128 v[6:9], v100 offset:272
	s_waitcnt lgkmcnt(11)
	ds_read_b128 v[10:13], v100 offset:512
	s_waitcnt lgkmcnt(11)
	ds_read_b128 v[14:17], v100 offset:528
	s_waitcnt lgkmcnt(11)
	ds_read_b128 v[34:37], v100 offset:768
	s_waitcnt lgkmcnt(11)
	ds_read_b128 v[38:41], v100 offset:784
	s_waitcnt lgkmcnt(11)
	ds_read_b128 v[26:29], v100 offset:1024
	s_waitcnt lgkmcnt(11)
	ds_read_b128 v[30:33], v100 offset:1040
	s_waitcnt lgkmcnt(11)
	ds_read_b32 v94, v101 offset:1280
	s_waitcnt lgkmcnt(11)
	ds_read_b64 v[96:97], v1 offset:1536
	s_lshl_b32 s6, s4, 4
	s_cmp_gt_u32 s4, 15
	s_cselect_b64 s[18:19], -1, 0
	s_mov_b64 s[48:49], -1
	s_and_b64 vcc, exec, s[18:19]
	s_cbranch_vccz .LBB0_855
	v_readlane_b32 s8, v254, 0
	s_sub_i32 s2, 0x8ff, s6
	s_add_i32 s3, s6, 0xffffff00
	v_readlane_b32 s9, v254, 1
	s_and_b64 s[10:11], s[8:9], exec
	s_cselect_b32 s2, s3, s2
	v_readlane_b32 s3, v254, 2
	s_add_i32 s46, s2, s3
	s_mov_b64 s[48:49], 0

.LBB0_857:
	s_ashr_i32 s47, s46, 31
	s_lshl_b64 s[10:11], s[46:47], 9
	v_lshl_add_u64 v[92:93], v[82:83], 0, s[10:11]
	s_mov_b32 s7, 0
	s_mov_b32 s10, -2
	s_mov_b32 s46, 0
	v_readlane_b32 s2, v254, 61
	v_readlane_b32 s3, v254, 62
	s_branch .LBB0_859

.LBB0_863:
	s_waitcnt lgkmcnt(0)
	s_barrier
	s_waitcnt lgkmcnt(11)
	ds_read_b128 v[22:25], v100 offset:25088
	s_waitcnt lgkmcnt(11)
	ds_read_b128 v[18:21], v100 offset:25104
	s_waitcnt lgkmcnt(11)
	ds_read_b128 v[2:5], v100 offset:25344
	s_waitcnt lgkmcnt(11)
	ds_read_b128 v[6:9], v100 offset:25360
	s_waitcnt lgkmcnt(11)
	ds_read_b128 v[10:13], v100 offset:25600
	s_waitcnt lgkmcnt(11)
	ds_read_b128 v[14:17], v100 offset:25616
	s_waitcnt lgkmcnt(11)
	ds_read_b128 v[34:37], v100 offset:25856
	s_waitcnt lgkmcnt(11)
	ds_read_b128 v[38:41], v100 offset:25872
	s_waitcnt lgkmcnt(11)
	ds_read_b128 v[26:29], v100 offset:26112
	s_waitcnt lgkmcnt(11)
	ds_read_b128 v[30:33], v100 offset:26128
	s_waitcnt lgkmcnt(11)
	ds_read_b32 v94, v101 offset:26368
	s_waitcnt lgkmcnt(11)
	ds_read_b64 v[96:97], v1 offset:26624
	s_or_b32 s7, s6, 16
	s_mov_b64 s[46:47], -1
	s_and_b64 vcc, exec, s[18:19]
	s_cbranch_vccz .LBB0_865
	v_readlane_b32 s8, v254, 0
	s_sub_i32 s2, 0x8ff, s7
	s_addk_i32 s6, 0xff10
	v_readlane_b32 s9, v254, 1
	s_and_b64 s[10:11], s[8:9], exec
	s_cselect_b32 s2, s6, s2
	v_readlane_b32 s3, v254, 2
	s_add_i32 s18, s2, s3
	s_mov_b64 s[46:47], 0

.LBB0_867:
	s_ashr_i32 s19, s18, 31
	s_lshl_b64 s[6:7], s[18:19], 9
	v_lshl_add_u64 v[92:93], v[82:83], 0, s[6:7]
	s_mov_b32 s6, 0
	s_mov_b32 s7, -2
	s_mov_b32 s18, 0
	v_readlane_b32 s2, v254, 61
	v_readlane_b32 s3, v254, 62
	s_branch .LBB0_869

.LBB0_900:
	s_waitcnt lgkmcnt(9)
	ds_read_b128 v[30:33], v94
	s_waitcnt lgkmcnt(9)
	ds_read_b128 v[26:29], v94 offset:16
	s_waitcnt lgkmcnt(9)
	ds_read_b128 v[22:25], v94 offset:32
	s_waitcnt lgkmcnt(9)
	ds_read_b128 v[18:21], v94 offset:48
	s_waitcnt lgkmcnt(9)
	ds_read_b128 v[2:5], v94 offset:256
	s_waitcnt lgkmcnt(9)
	ds_read_b128 v[6:9], v94 offset:272
	s_waitcnt lgkmcnt(7)
	ds_read_b32 v73, v95 offset:512
	s_waitcnt lgkmcnt(7)
	ds_read_b128 v[34:37], v1 offset:768
	ds_read_b128 v[14:17], v94 offset:288
	ds_read_b128 v[10:13], v94 offset:304
	s_lshl_b32 s6, s4, 4
	s_cmp_gt_u32 s4, 15
	s_cselect_b64 s[16:17], -1, 0
	s_mov_b64 s[46:47], -1
	s_and_b64 vcc, exec, s[16:17]
	s_cbranch_vccz .LBB0_902
	v_readlane_b32 s8, v254, 7
	s_sub_i32 s2, 0x8ff, s6
	s_add_i32 s3, s6, 0xffffff00
	v_readlane_b32 s9, v254, 8
	s_and_b64 s[10:11], s[8:9], exec
	s_cselect_b32 s2, s3, s2
	v_readlane_b32 s3, v254, 10
	s_add_i32 s18, s2, s3
	s_mov_b64 s[46:47], 0

.LBB0_904:
	s_ashr_i32 s19, s18, 31
	s_lshl_b64 s[10:11], s[18:19], 9
	v_lshl_add_u64 v[92:93], v[76:77], 0, s[10:11]
	s_mov_b32 s7, 0
	s_mov_b32 s10, -2
	s_mov_b32 s18, 0
	s_branch .LBB0_906

.LBB0_910:
	s_waitcnt lgkmcnt(0)
	s_barrier
	s_waitcnt lgkmcnt(9)
	ds_read_b128 v[30:33], v94 offset:12800
	s_waitcnt lgkmcnt(9)
	ds_read_b128 v[26:29], v94 offset:12816
	s_waitcnt lgkmcnt(9)
	ds_read_b128 v[22:25], v94 offset:12832
	s_waitcnt lgkmcnt(9)
	ds_read_b128 v[18:21], v94 offset:12848
	s_waitcnt lgkmcnt(9)
	ds_read_b128 v[2:5], v94 offset:13056
	s_waitcnt lgkmcnt(9)
	ds_read_b128 v[6:9], v94 offset:13072
	s_waitcnt lgkmcnt(7)
	ds_read_b32 v73, v95 offset:13312
	s_waitcnt lgkmcnt(7)
	ds_read_b128 v[34:37], v1 offset:13568
	ds_read_b128 v[14:17], v94 offset:13088
	ds_read_b128 v[10:13], v94 offset:13104
	s_or_b32 s7, s6, 16
	s_mov_b64 s[18:19], -1
	s_and_b64 vcc, exec, s[16:17]
	s_cbranch_vccz .LBB0_912
	v_readlane_b32 s8, v254, 7
	s_sub_i32 s2, 0x8ff, s7
	s_addk_i32 s6, 0xff10
	v_readlane_b32 s9, v254, 8
	s_and_b64 s[10:11], s[8:9], exec
	s_cselect_b32 s2, s6, s2
	v_readlane_b32 s3, v254, 10
	s_add_i32 s16, s2, s3
	s_mov_b64 s[18:19], 0

.LBB0_914:
	s_ashr_i32 s17, s16, 31
	s_lshl_b64 s[6:7], s[16:17], 9
	v_lshl_add_u64 v[92:93], v[76:77], 0, s[6:7]
	s_mov_b32 s16, 0
	s_mov_b32 s6, -2
	s_movk_i32 s7, 0x3520
	s_branch .LBB0_916
